# attention softmax: row-max over the 32 scores as 16 v_max3 ops on 4 chains (drops 32 self-max canonicalisations per tile)
# speedup vs baseline: 1.0235x; 1.0235x over previous
; __device__ __forceinline__ void attn_phase(LAS unsigned char* lds, const bf16* Q, const bf16* KV, const bf16* KPE, const float* rope, bf16* mix, int bid, int G, int tid) {
;     ...
;                 float mx = fmaxf(S0[0], S1[0]);
; #pragma unroll
;                 for (int e = 1; e < 16; ++e) mx = fmaxf(mx, fmaxf(S0[e], S1[e]));
;                 mx = fmaxf(mx, __shfl_xor(mx, 32));
.LBB0_256:
	s_nop 9
	v_max3_f32 v209, v64, v65, v66
	v_max3_f32 v210, v67, v68, v69
	v_max3_f32 v211, v70, v71, v72
	v_max3_f32 v212, v73, v74, v75
	v_max3_f32 v209, v209, v76, v77
	v_max3_f32 v210, v210, v78, v79
	v_max3_f32 v211, v211, v80, v81
	v_max3_f32 v212, v212, v82, v83
	v_max3_f32 v209, v209, v84, v85
	v_max3_f32 v210, v210, v86, v87
	v_max3_f32 v211, v211, v88, v89
	v_max3_f32 v212, v212, v90, v91
	v_max3_f32 v209, v209, v92, v93
	v_max3_f32 v210, v210, v94, v95
	v_max3_f32 v209, v209, v210, v211
	v_max_f32_e32 v209, v209, v212
	v_and_b32_e32 v211, 64, v220
	v_xor_b32_e32 v210, 32, v220
	v_add_u32_e32 v211, 64, v211
	v_cmp_lt_i32_e32 vcc, v210, v211
	s_nop 1
	v_cndmask_b32_e32 v210, v220, v210, vcc
	v_lshlrev_b32_e32 v210, 2, v210
	ds_bpermute_b32 v210, v210, v209
	s_waitcnt lgkmcnt(0)
	v_max_f32_e32 v210, v210, v210
	v_max_f32_e32 v209, v209, v210
	v_add_f32_e32 v210, 0x40c00000, v184
	v_cmp_gt_f32_e32 vcc, v209, v210
	s_nop 1
	v_cndmask_b32_e32 v209, v184, v209, vcc
	v_sub_f32_e32 v184, v184, v209
	v_exp_f32_e32 v184, v184
	s_nop 0
	v_cmp_neq_f32_e32 vcc, 1.0, v184
	s_cbranch_vccz .LBB0_258
	v_pk_mul_f32 v[62:63], v[62:63], v[184:185] op_sel_hi:[1,0]
	v_pk_mul_f32 v[60:61], v[60:61], v[184:185] op_sel_hi:[1,0]
	v_pk_mul_f32 v[58:59], v[58:59], v[184:185] op_sel_hi:[1,0]
	v_pk_mul_f32 v[56:57], v[56:57], v[184:185] op_sel_hi:[1,0]
	v_pk_mul_f32 v[54:55], v[54:55], v[184:185] op_sel_hi:[1,0]
	v_pk_mul_f32 v[52:53], v[52:53], v[184:185] op_sel_hi:[1,0]
	v_pk_mul_f32 v[50:51], v[50:51], v[184:185] op_sel_hi:[1,0]
	v_pk_mul_f32 v[48:49], v[48:49], v[184:185] op_sel_hi:[1,0]
	v_pk_mul_f32 v[46:47], v[46:47], v[184:185] op_sel_hi:[1,0]
	v_pk_mul_f32 v[44:45], v[44:45], v[184:185] op_sel_hi:[1,0]
	v_pk_mul_f32 v[42:43], v[42:43], v[184:185] op_sel_hi:[1,0]
	v_pk_mul_f32 v[40:41], v[40:41], v[184:185] op_sel_hi:[1,0]
	v_pk_mul_f32 v[38:39], v[38:39], v[184:185] op_sel_hi:[1,0]
	v_pk_mul_f32 v[36:37], v[36:37], v[184:185] op_sel_hi:[1,0]
	v_pk_mul_f32 v[34:35], v[34:35], v[184:185] op_sel_hi:[1,0]
	v_pk_mul_f32 v[32:33], v[32:33], v[184:185] op_sel_hi:[1,0]
	v_pk_mul_f32 v[30:31], v[30:31], v[184:185] op_sel_hi:[1,0]
	v_pk_mul_f32 v[28:29], v[28:29], v[184:185] op_sel_hi:[1,0]
	v_pk_mul_f32 v[26:27], v[26:27], v[184:185] op_sel_hi:[1,0]
	v_pk_mul_f32 v[24:25], v[24:25], v[184:185] op_sel_hi:[1,0]
	v_pk_mul_f32 v[22:23], v[22:23], v[184:185] op_sel_hi:[1,0]
	v_pk_mul_f32 v[20:21], v[20:21], v[184:185] op_sel_hi:[1,0]
	v_pk_mul_f32 v[18:19], v[18:19], v[184:185] op_sel_hi:[1,0]
	v_pk_mul_f32 v[16:17], v[16:17], v[184:185] op_sel_hi:[1,0]
	v_pk_mul_f32 v[14:15], v[14:15], v[184:185] op_sel_hi:[1,0]
	v_pk_mul_f32 v[12:13], v[12:13], v[184:185] op_sel_hi:[1,0]
	v_pk_mul_f32 v[10:11], v[10:11], v[184:185] op_sel_hi:[1,0]
	v_pk_mul_f32 v[8:9], v[8:9], v[184:185] op_sel_hi:[1,0]
	v_pk_mul_f32 v[6:7], v[6:7], v[184:185] op_sel_hi:[1,0]
	v_pk_mul_f32 v[4:5], v[4:5], v[184:185] op_sel_hi:[1,0]
	v_pk_mul_f32 v[2:3], v[2:3], v[184:185] op_sel_hi:[1,0]
	v_pk_mul_f32 v[0:1], v[0:1], v[184:185] op_sel_hi:[1,0]
